# SWA item epilogue: 4 sink loads issued up front, no waits on the O stores
# baseline (speedup 1.0000x reference)
; __device__ __forceinline__ unsigned pkbf(float lo, float hi) { f32x2_t v = {lo, hi}; bf16x2_t b = __builtin_convertvector(v, bf16x2_t); return __builtin_bit_cast(unsigned, b); }
; __device__ __forceinline__ void store_group(const f32x4 (&Og)[4], float inv, bf16_t* orow, int g) {
; #pragma unroll
;     for (int db = 0; db < 4; ++db) { u32x2 w; w.x = pkbf(Og[db][0] * inv, Og[db][1] * inv); w.y = pkbf(Og[db][2] * inv, Og[db][3] * inv);
;         *(u32x2*)(orow + 16 * db + 4 * g) = w; }
; __device__ __forceinline__ void swa_phase(LAS unsigned char* lds, const bf16_t* Q, const bf16_t* K, const bf16_t* V, bf16_t* Ob, const float* sink, float negb) {
;     ...
;         for (int grp = 0; grp < 4; ++grp) { const float lt = red_sum4(ls[grp]) + __builtin_amdgcn_exp2f(sink[4 * kvh + grp] * LOG2E + negb);
;             store_group(O[grp], __builtin_amdgcn_rcpf(lt), Ob + qrow * DM + (4 * kvh + grp) * 64, g); }
.LBB0_342:
	s_lshl_b32 s82, s42, 4
	v_lshl_add_u64 v[6:7], v[120:121], 0, s[82:83]
	flat_load_dword v4, v[6:7]
	flat_load_dword v100, v[6:7] offset:4
	flat_load_dword v102, v[6:7] offset:8
	flat_load_dword v103, v[6:7] offset:12
	v_mov_b32_e32 v5, v131
	s_mov_b32 s0, 0x3fb8aa3b
	s_nop 0
	v_permlane16_swap_b32_e32 v131, v5
	v_add_f32_e32 v5, v131, v5
	v_mov_b32_e32 v8, v5
	s_nop 1
	v_permlane32_swap_b32_e32 v5, v8
	v_add_f32_e32 v5, v5, v8
	s_lshl_b32 s82, s37, 1
	v_readlane_b32 s52, v240, 27
	v_readlane_b32 s50, v240, 29
	s_add_i32 s41, s41, 1
	v_readlane_b32 s53, v240, 28
	v_readlane_b32 s51, v240, 30
	s_waitcnt vmcnt(0) lgkmcnt(0)
	v_fma_f32 v4, v4, s0, -v186
	v_exp_f32_e32 v4, v4
	s_nop 0
	v_add_f32_e32 v4, v5, v4
	v_rcp_f32_e32 v8, v4
	v_lshl_add_u64 v[4:5], v[124:125], 0, v[126:127]
	v_lshl_add_u64 v[10:11], v[4:5], 0, s[82:83]
	s_or_b32 s82, s36, 0x80
	v_pk_mul_f32 v[12:13], v[64:65], v[8:9] op_sel_hi:[1,0]
	v_pk_mul_f32 v[14:15], v[66:67], v[8:9] op_sel_hi:[1,0]
	v_pk_mul_f32 v[16:17], v[60:61], v[8:9] op_sel_hi:[1,0]
	v_pk_mul_f32 v[18:19], v[62:63], v[8:9] op_sel_hi:[1,0]
	v_pk_mul_f32 v[20:21], v[56:57], v[8:9] op_sel_hi:[1,0]
	v_pk_mul_f32 v[22:23], v[58:59], v[8:9] op_sel_hi:[1,0]
	v_pk_mul_f32 v[24:25], v[52:53], v[8:9] op_sel_hi:[1,0]
	v_pk_mul_f32 v[8:9], v[54:55], v[8:9] op_sel_hi:[1,0]
	v_cvt_pk_bf16_f32 v12, v12, v13
	v_cvt_pk_bf16_f32 v13, v14, v15
	v_cvt_pk_bf16_f32 v14, v16, v17
	v_cvt_pk_bf16_f32 v15, v18, v19
	v_cvt_pk_bf16_f32 v16, v20, v21
	v_cvt_pk_bf16_f32 v17, v22, v23
	v_cvt_pk_bf16_f32 v18, v24, v25
	v_cvt_pk_bf16_f32 v19, v8, v9
	global_store_dwordx2 v[10:11], v[12:13], off
	global_store_dwordx2 v[10:11], v[14:15], off offset:32
	global_store_dwordx2 v[10:11], v[16:17], off offset:64
	global_store_dwordx2 v[10:11], v[18:19], off offset:96
	v_mov_b32_e32 v8, v100
	v_mov_b32_e32 v9, v130
	s_nop 1
	v_permlane16_swap_b32_e32 v130, v9
	v_add_f32_e32 v9, v130, v9
	v_mov_b32_e32 v10, v9
	s_nop 1
	v_permlane32_swap_b32_e32 v9, v10
	v_add_f32_e32 v9, v9, v10
	v_lshl_add_u64 v[10:11], v[4:5], 0, s[82:83]
	s_or_b32 s82, s36, 0x100
	v_fma_f32 v8, v8, s0, -v186
	v_exp_f32_e32 v8, v8
	s_nop 0
	v_add_f32_e32 v8, v9, v8
	v_rcp_f32_e32 v8, v8
	s_nop 0
	v_pk_mul_f32 v[12:13], v[48:49], v[8:9] op_sel_hi:[1,0]
	v_pk_mul_f32 v[14:15], v[50:51], v[8:9] op_sel_hi:[1,0]
	v_pk_mul_f32 v[16:17], v[44:45], v[8:9] op_sel_hi:[1,0]
	v_pk_mul_f32 v[18:19], v[46:47], v[8:9] op_sel_hi:[1,0]
	v_pk_mul_f32 v[20:21], v[40:41], v[8:9] op_sel_hi:[1,0]
	v_pk_mul_f32 v[22:23], v[42:43], v[8:9] op_sel_hi:[1,0]
	v_pk_mul_f32 v[24:25], v[36:37], v[8:9] op_sel_hi:[1,0]
	v_pk_mul_f32 v[8:9], v[38:39], v[8:9] op_sel_hi:[1,0]
	v_cvt_pk_bf16_f32 v12, v12, v13
	v_cvt_pk_bf16_f32 v13, v14, v15
	v_cvt_pk_bf16_f32 v14, v16, v17
	v_cvt_pk_bf16_f32 v15, v18, v19
	v_cvt_pk_bf16_f32 v16, v20, v21
	v_cvt_pk_bf16_f32 v17, v22, v23
	v_cvt_pk_bf16_f32 v18, v24, v25
	v_cvt_pk_bf16_f32 v19, v8, v9
	global_store_dwordx2 v[10:11], v[12:13], off
	global_store_dwordx2 v[10:11], v[14:15], off offset:32
	global_store_dwordx2 v[10:11], v[16:17], off offset:64
	global_store_dwordx2 v[10:11], v[18:19], off offset:96
	v_mov_b32_e32 v8, v102
	v_mov_b32_e32 v9, v129
	s_nop 1
	v_permlane16_swap_b32_e32 v129, v9
	v_add_f32_e32 v9, v129, v9
	v_mov_b32_e32 v10, v9
	s_nop 1
	v_permlane32_swap_b32_e32 v9, v10
	v_add_f32_e32 v9, v9, v10
	v_lshl_add_u64 v[10:11], v[4:5], 0, s[82:83]
	s_or_b32 s82, s36, 0x180
	v_lshl_add_u64 v[4:5], v[4:5], 0, s[82:83]
	v_fma_f32 v8, v8, s0, -v186
	v_exp_f32_e32 v8, v8
	s_nop 0
	v_add_f32_e32 v8, v9, v8
	v_rcp_f32_e32 v8, v8
	s_nop 0
	v_pk_mul_f32 v[12:13], v[72:73], v[8:9] op_sel_hi:[1,0]
	v_pk_mul_f32 v[14:15], v[74:75], v[8:9] op_sel_hi:[1,0]
	v_pk_mul_f32 v[16:17], v[84:85], v[8:9] op_sel_hi:[1,0]
	v_pk_mul_f32 v[18:19], v[86:87], v[8:9] op_sel_hi:[1,0]
	v_pk_mul_f32 v[20:21], v[88:89], v[8:9] op_sel_hi:[1,0]
	v_pk_mul_f32 v[22:23], v[90:91], v[8:9] op_sel_hi:[1,0]
	v_pk_mul_f32 v[24:25], v[96:97], v[8:9] op_sel_hi:[1,0]
	v_pk_mul_f32 v[8:9], v[98:99], v[8:9] op_sel_hi:[1,0]
	v_cvt_pk_bf16_f32 v12, v12, v13
	v_cvt_pk_bf16_f32 v13, v14, v15
	v_cvt_pk_bf16_f32 v14, v16, v17
	v_cvt_pk_bf16_f32 v15, v18, v19
	v_cvt_pk_bf16_f32 v16, v20, v21
	v_cvt_pk_bf16_f32 v17, v22, v23
	v_cvt_pk_bf16_f32 v18, v24, v25
	v_cvt_pk_bf16_f32 v19, v8, v9
	global_store_dwordx2 v[10:11], v[12:13], off
	global_store_dwordx2 v[10:11], v[14:15], off offset:32
	global_store_dwordx2 v[10:11], v[16:17], off offset:64
	global_store_dwordx2 v[10:11], v[18:19], off offset:96
	v_mov_b32_e32 v6, v103
	v_mov_b32_e32 v7, v128
	s_nop 1
	v_permlane16_swap_b32_e32 v128, v7
	v_add_f32_e32 v7, v128, v7
	v_mov_b32_e32 v8, v7
	s_nop 1
	v_permlane32_swap_b32_e32 v7, v8
	v_add_f32_e32 v7, v7, v8
	v_fma_f32 v6, v6, s0, -v186
	v_exp_f32_e32 v6, v6
	s_nop 0
	v_add_f32_e32 v6, v7, v6
	v_rcp_f32_e32 v6, v6
	s_nop 0
	v_pk_mul_f32 v[8:9], v[68:69], v[6:7] op_sel_hi:[1,0]
	v_pk_mul_f32 v[10:11], v[70:71], v[6:7] op_sel_hi:[1,0]
	v_pk_mul_f32 v[12:13], v[76:77], v[6:7] op_sel_hi:[1,0]
	v_pk_mul_f32 v[14:15], v[78:79], v[6:7] op_sel_hi:[1,0]
	v_pk_mul_f32 v[16:17], v[80:81], v[6:7] op_sel_hi:[1,0]
	v_pk_mul_f32 v[18:19], v[82:83], v[6:7] op_sel_hi:[1,0]
	v_pk_mul_f32 v[20:21], v[92:93], v[6:7] op_sel_hi:[1,0]
	v_pk_mul_f32 v[6:7], v[94:95], v[6:7] op_sel_hi:[1,0]
	v_cvt_pk_bf16_f32 v8, v8, v9
	v_cvt_pk_bf16_f32 v9, v10, v11
	v_cvt_pk_bf16_f32 v10, v12, v13
	v_cvt_pk_bf16_f32 v11, v14, v15
	v_cvt_pk_bf16_f32 v12, v16, v17
	v_cvt_pk_bf16_f32 v13, v18, v19
	v_cvt_pk_bf16_f32 v14, v20, v21
	v_cvt_pk_bf16_f32 v15, v6, v7
	global_store_dwordx2 v[4:5], v[8:9], off
	global_store_dwordx2 v[4:5], v[10:11], off offset:32
	global_store_dwordx2 v[4:5], v[12:13], off offset:64
	global_store_dwordx2 v[4:5], v[14:15], off offset:96
